# A3 (decay prefix sums and chunk operands) rewritten by hand with op-type batching and DPP tree sums; A1 loads hoisted; A6 row-split
# speedup vs baseline: 1.0402x; 1.0176x over previous
; #define LAS __attribute__((address_space(3)))
; __device__ __forceinline__ void unpack8(u32x4 u, float* f) { f[0] = bflo(u.x); f[1] = bfhi(u.x); f[2] = bflo(u.y); f[3] = bfhi(u.y); f[4] = bflo(u.z); f[5] = bfhi(u.z); f[6] = bflo(u.w); f[7] = bfhi(u.w); }
; __device__ __forceinline__ void chunkA_item(const Args& A, LAS unsigned char* lds, int tid, int lane, int wave, int ci, int ci_next, HeadConstA& H) {
;     ...
;     {
;         const int t = tid >> 3, part = tid & 7; const bool first = (c == 0 && t == 0);
;         const bf16_t* zr = Z + (row0 + t) * NZ; const bf16_t* zp = zr - NZ;
; #pragma unroll
;         for (int s = 0; s < 5; ++s) {
;             const int zcol = (s == 0 ? h * 64 : s == 1 ? 512 + h * 64 : s == 2 ? 1024 + h * 64 : s == 3 ? 1536 : 1600) + part * 8;
;             const u32x4 cu = *(const u32x4*)(zr + zcol); u32x4 pu = {0u, 0u, 0u, 0u}; if (!first) pu = *(const u32x4*)(zp + zcol);
;             const f32x4 m0 = *(const f32x4*)(A.mu + zcol), m1 = *(const f32x4*)(A.mu + zcol + 4);
;             float cur[8], prv[8], o[8]; unpack8(cu, cur); unpack8(pu, prv);
;             const float mu[8] = {m0.x, m0.y, m0.z, m0.w, m1.x, m1.y, m1.z, m1.w};
; #pragma unroll
;             for (int i = 0; i < 8; ++i) o[i] = cur[i] + mu[i] * (prv[i] - cur[i]);
;             if (s < 3) { LAS f32x4* dst = (LAS f32x4*)(lds + s * 16384 + (t * 64 + part * 8) * 4); dst[0] = (f32x4){o[0], o[1], o[2], o[3]}; dst[1] = (f32x4){o[4], o[5], o[6], o[7]}; }
.LBB0_149:
	s_andn2_b64 vcc, exec, s[24:25]
	s_cbranch_vccnz .LBB0_151
	v_mov_b64_e32 v[0:1], v[60:61]
	v_mov_b64_e32 v[4:5], v[56:57]
	v_mov_b64_e32 v[16:17], v[52:53]
	v_mov_b64_e32 v[20:21], v[48:49]
	v_mov_b64_e32 v[8:9], v[44:45]
	v_mov_b64_e32 v[12:13], v[40:41]
	v_mov_b64_e32 v[24:25], v[36:37]
	v_mov_b64_e32 v[28:29], v[32:33]
	s_lshl_b32 s30, s29, 6
	s_mov_b32 s23, s29
	v_mov_b64_e32 v[2:3], v[62:63]
	v_mov_b64_e32 v[6:7], v[58:59]
	v_mov_b64_e32 v[18:19], v[54:55]
	v_mov_b64_e32 v[22:23], v[50:51]
	v_mov_b64_e32 v[10:11], v[46:47]
	v_mov_b64_e32 v[14:15], v[42:43]
	v_mov_b64_e32 v[26:27], v[38:39]
	v_mov_b64_e32 v[30:31], v[34:35]
	v_mov_b32_e32 v203, v70
	v_mov_b32_e32 v208, v69
	v_mov_b32_e32 v209, v68
	v_mov_b32_e32 v210, v67
	v_mov_b32_e32 v211, v66
	v_mov_b32_e32 v212, v65
	v_mov_b32_e32 v213, v64
.LBB0_151:
	s_ashr_i32 s24, s28, 8
	s_and_b32 s29, s28, 31
	s_ashr_i32 s25, s24, 31
	s_lshl_b64 s[24:25], s[24:25], 11
	v_lshl_add_u32 v72, s29, 6, v147
	v_lshl_add_u64 v[108:109], s[24:25], 0, v[72:73]
	v_mov_b64_e32 v[110:111], s[94:95]
	v_mad_u64_u32 v[222:223], s[24:25], v108, s22, v[110:111]
	v_mad_i32_i24 v223, v109, s22, v223
	v_or_b32_e32 v72, s30, v78
	v_lshl_add_u64 v[108:109], v[72:73], 1, v[222:223]
	global_load_dwordx4 v[32:35], v[108:109], off
	global_load_dwordx4 v[36:39], v[108:109], off offset:1024
	global_load_dwordx4 v[40:43], v[108:109], off offset:2048
	v_lshl_add_u64 v[112:113], v[72:73], 2, s[60:61]
	v_or_b32_e32 v72, 0x400, v72
	v_lshl_add_u64 v[184:185], v[72:73], 2, s[60:61]
	v_lshlrev_b32_e32 v72, 1, v78
	v_lshl_add_u64 v[110:111], v[222:223], 0, v[72:73]
	global_load_dwordx4 v[44:47], v[110:111], off offset:3072
	global_load_dwordx4 v[48:51], v[110:111], off offset:3200
	s_cmp_lg_u32 s29, 0
	s_cselect_b64 s[24:25], -1, 0
	s_or_b64 s[78:79], s[24:25], s[26:27]
	s_movk_i32 s24, 0xe400
	s_mov_b32 s25, -1
	v_lshl_add_u64 v[108:109], v[108:109], 0, s[24:25]
	v_mov_b32_e32 v52, 0
	v_mov_b32_e32 v53, 0
	v_mov_b32_e32 v54, 0
	v_mov_b32_e32 v55, 0
	v_mov_b32_e32 v56, 0
	v_mov_b32_e32 v57, 0
	v_mov_b32_e32 v58, 0
	v_mov_b32_e32 v59, 0
	v_mov_b32_e32 v60, 0
	v_mov_b32_e32 v61, 0
	v_mov_b32_e32 v62, 0
	v_mov_b32_e32 v63, 0
	v_mov_b32_e32 v64, 0
	v_mov_b32_e32 v65, 0
	v_mov_b32_e32 v66, 0
	v_mov_b32_e32 v67, 0
	v_mov_b32_e32 v68, 0
	v_mov_b32_e32 v69, 0
	v_mov_b32_e32 v70, 0
	v_mov_b32_e32 v71, 0
	s_and_saveexec_b64 s[24:25], s[78:79]
	global_load_dwordx4 v[52:55], v[108:109], off
	global_load_dwordx4 v[56:59], v[108:109], off offset:1024
	global_load_dwordx4 v[60:63], v[108:109], off offset:2048
	global_load_dwordx4 v[64:67], v[110:111], off offset:-4096
	global_load_dwordx4 v[68:71], v[110:111], off offset:-3968
	s_or_b64 exec, exec, s[24:25]
	global_load_dwordx4 v[214:217], v[112:113], off
	global_load_dwordx4 v[218:221], v[112:113], off offset:16
	global_load_dwordx4 v[226:229], v[112:113], off offset:2048
	global_load_dwordx4 v[230:233], v[112:113], off offset:2064
	s_waitcnt vmcnt(2)
	v_lshlrev_b32_e32 v108, 16, v32
	v_and_b32_e32 v109, 0xffff0000, v32
	v_lshlrev_b32_e32 v110, 16, v33
	v_and_b32_e32 v111, 0xffff0000, v33
	v_lshlrev_b32_e32 v112, 16, v52
	v_and_b32_e32 v113, 0xffff0000, v52
	v_lshlrev_b32_e32 v250, 16, v53
	v_and_b32_e32 v251, 0xffff0000, v53
	v_lshlrev_b32_e32 v252, 16, v34
	v_and_b32_e32 v253, 0xffff0000, v34
	v_lshlrev_b32_e32 v254, 16, v35
	v_and_b32_e32 v255, 0xffff0000, v35
	v_lshlrev_b32_e32 v222, 16, v54
	v_and_b32_e32 v223, 0xffff0000, v54
	v_lshlrev_b32_e32 v32, 16, v55
	v_and_b32_e32 v33, 0xffff0000, v55
	v_pk_add_f32 v[112:113], v[112:113], v[108:109] neg_lo:[0,1] neg_hi:[0,1]
	v_pk_add_f32 v[250:251], v[250:251], v[110:111] neg_lo:[0,1] neg_hi:[0,1]
	v_pk_add_f32 v[222:223], v[222:223], v[252:253] neg_lo:[0,1] neg_hi:[0,1]
	v_pk_add_f32 v[32:33], v[32:33], v[254:255] neg_lo:[0,1] neg_hi:[0,1]
	v_pk_fma_f32 v[214:215], v[214:215], v[112:113], v[108:109]
	v_pk_fma_f32 v[216:217], v[216:217], v[250:251], v[110:111]
	v_pk_fma_f32 v[218:219], v[218:219], v[222:223], v[252:253]
	v_pk_fma_f32 v[220:221], v[220:221], v[32:33], v[254:255]
	ds_write_b128 v197, v[214:217] offset:0
	ds_write_b128 v197, v[218:221] offset:16
	global_load_dwordx4 v[214:217], v[184:185], off
	global_load_dwordx4 v[218:221], v[184:185], off offset:16
	s_waitcnt vmcnt(2)
	v_lshlrev_b32_e32 v108, 16, v36
	v_and_b32_e32 v109, 0xffff0000, v36
	v_lshlrev_b32_e32 v110, 16, v37
	v_and_b32_e32 v111, 0xffff0000, v37
	v_lshlrev_b32_e32 v112, 16, v56
	v_and_b32_e32 v113, 0xffff0000, v56
	v_lshlrev_b32_e32 v250, 16, v57
	v_and_b32_e32 v251, 0xffff0000, v57
	v_lshlrev_b32_e32 v252, 16, v38
	v_and_b32_e32 v253, 0xffff0000, v38
	v_lshlrev_b32_e32 v254, 16, v39
	v_and_b32_e32 v255, 0xffff0000, v39
	v_lshlrev_b32_e32 v222, 16, v58
	v_and_b32_e32 v223, 0xffff0000, v58
	v_lshlrev_b32_e32 v36, 16, v59
	v_and_b32_e32 v37, 0xffff0000, v59
	v_pk_add_f32 v[112:113], v[112:113], v[108:109] neg_lo:[0,1] neg_hi:[0,1]
	v_pk_add_f32 v[250:251], v[250:251], v[110:111] neg_lo:[0,1] neg_hi:[0,1]
	v_pk_add_f32 v[222:223], v[222:223], v[252:253] neg_lo:[0,1] neg_hi:[0,1]
	v_pk_add_f32 v[36:37], v[36:37], v[254:255] neg_lo:[0,1] neg_hi:[0,1]
	v_pk_fma_f32 v[226:227], v[226:227], v[112:113], v[108:109]
	v_pk_fma_f32 v[228:229], v[228:229], v[250:251], v[110:111]
	v_pk_fma_f32 v[230:231], v[230:231], v[222:223], v[252:253]
	v_pk_fma_f32 v[232:233], v[232:233], v[36:37], v[254:255]
	ds_write_b128 v197, v[226:229] offset:16384
	ds_write_b128 v197, v[230:233] offset:16400
	global_load_dwordx4 v[226:229], v[80:81], off
	global_load_dwordx4 v[230:233], v[80:81], off offset:16
	s_waitcnt vmcnt(2)
; #define LAS __attribute__((address_space(3)))
; __device__ __forceinline__ u32x4 pack8(const float* f) { u32x4 o; o.x = pk2(f[0], f[1]); o.y = pk2(f[2], f[3]); o.z = pk2(f[4], f[5]); o.w = pk2(f[6], f[7]); return o; }
; #define LBAR() asm volatile("s_waitcnt lgkmcnt(0)\n\ts_barrier" ::: "memory")
; __device__ __forceinline__ void chunkA_item(const Args& A, LAS unsigned char* lds, int tid, int lane, int wave, int ci, int ci_next, HeadConstA& H) {
;     ...
;             for (int i = 0; i < 8; ++i) o[i] = cur[i] + mu[i] * (prv[i] - cur[i]);
;             if (s < 3) { LAS f32x4* dst = (LAS f32x4*)(lds + s * 16384 + (t * 64 + part * 8) * 4); dst[0] = (f32x4){o[0], o[1], o[2], o[3]}; dst[1] = (f32x4){o[4], o[5], o[6], o[7]}; }
;             else { if (s == 3) {
; #pragma unroll
;                     for (int i = 0; i < 8; ++i) o[i] = 1.f - 2.f * __builtin_amdgcn_rcpf(1.f + __expf(2.f * o[i])); }
;                 *(LAS u32x4*)(lds + (s == 3 ? CA_TH : CA_AD) + t * 144 + part * 16) = pack8(o); }
;         }
;     }
;     LBAR();
	v_lshlrev_b32_e32 v108, 16, v40
	v_and_b32_e32 v109, 0xffff0000, v40
	v_lshlrev_b32_e32 v110, 16, v41
	v_and_b32_e32 v111, 0xffff0000, v41
	v_lshlrev_b32_e32 v112, 16, v60
	v_and_b32_e32 v113, 0xffff0000, v60
	v_lshlrev_b32_e32 v250, 16, v61
	v_and_b32_e32 v251, 0xffff0000, v61
	v_lshlrev_b32_e32 v252, 16, v42
	v_and_b32_e32 v253, 0xffff0000, v42
	v_lshlrev_b32_e32 v254, 16, v43
	v_and_b32_e32 v255, 0xffff0000, v43
	v_lshlrev_b32_e32 v222, 16, v62
	v_and_b32_e32 v223, 0xffff0000, v62
	v_lshlrev_b32_e32 v40, 16, v63
	v_and_b32_e32 v41, 0xffff0000, v63
	v_pk_add_f32 v[112:113], v[112:113], v[108:109] neg_lo:[0,1] neg_hi:[0,1]
	v_pk_add_f32 v[250:251], v[250:251], v[110:111] neg_lo:[0,1] neg_hi:[0,1]
	v_pk_add_f32 v[222:223], v[222:223], v[252:253] neg_lo:[0,1] neg_hi:[0,1]
	v_pk_add_f32 v[40:41], v[40:41], v[254:255] neg_lo:[0,1] neg_hi:[0,1]
	v_pk_fma_f32 v[214:215], v[214:215], v[112:113], v[108:109]
	v_pk_fma_f32 v[216:217], v[216:217], v[250:251], v[110:111]
	v_pk_fma_f32 v[218:219], v[218:219], v[222:223], v[252:253]
	v_pk_fma_f32 v[220:221], v[220:221], v[40:41], v[254:255]
	ds_write_b128 v197, v[214:217] offset:32768
	ds_write_b128 v197, v[218:221] offset:32784
	global_load_dwordx4 v[214:217], v[82:83], off
	global_load_dwordx4 v[218:221], v[82:83], off offset:16
	s_waitcnt vmcnt(2)
	v_lshlrev_b32_e32 v108, 16, v44
	v_and_b32_e32 v109, 0xffff0000, v44
	v_lshlrev_b32_e32 v110, 16, v45
	v_and_b32_e32 v111, 0xffff0000, v45
	v_lshlrev_b32_e32 v112, 16, v64
	v_and_b32_e32 v113, 0xffff0000, v64
	v_lshlrev_b32_e32 v250, 16, v65
	v_and_b32_e32 v251, 0xffff0000, v65
	v_lshlrev_b32_e32 v252, 16, v46
	v_and_b32_e32 v253, 0xffff0000, v46
	v_lshlrev_b32_e32 v254, 16, v47
	v_and_b32_e32 v255, 0xffff0000, v47
	v_lshlrev_b32_e32 v222, 16, v66
	v_and_b32_e32 v223, 0xffff0000, v66
	v_lshlrev_b32_e32 v44, 16, v67
	v_and_b32_e32 v45, 0xffff0000, v67
	v_pk_add_f32 v[112:113], v[112:113], v[108:109] neg_lo:[0,1] neg_hi:[0,1]
	v_pk_add_f32 v[250:251], v[250:251], v[110:111] neg_lo:[0,1] neg_hi:[0,1]
	v_pk_add_f32 v[222:223], v[222:223], v[252:253] neg_lo:[0,1] neg_hi:[0,1]
	v_pk_add_f32 v[44:45], v[44:45], v[254:255] neg_lo:[0,1] neg_hi:[0,1]
	v_pk_fma_f32 v[226:227], v[226:227], v[112:113], v[108:109]
	v_pk_fma_f32 v[228:229], v[228:229], v[250:251], v[110:111]
	v_pk_fma_f32 v[230:231], v[230:231], v[222:223], v[252:253]
	v_pk_fma_f32 v[232:233], v[232:233], v[44:45], v[254:255]
	v_add_f32_e32 v226, v226, v226
	v_add_f32_e32 v227, v227, v227
	v_add_f32_e32 v228, v228, v228
	v_add_f32_e32 v229, v229, v229
	v_add_f32_e32 v230, v230, v230
	v_add_f32_e32 v231, v231, v231
	v_add_f32_e32 v232, v232, v232
	v_add_f32_e32 v233, v233, v233
	v_mul_f32_e32 v226, 0x3fb8aa3b, v226
	v_mul_f32_e32 v227, 0x3fb8aa3b, v227
	v_mul_f32_e32 v228, 0x3fb8aa3b, v228
	v_mul_f32_e32 v229, 0x3fb8aa3b, v229
	v_mul_f32_e32 v230, 0x3fb8aa3b, v230
	v_mul_f32_e32 v231, 0x3fb8aa3b, v231
	v_mul_f32_e32 v232, 0x3fb8aa3b, v232
	v_mul_f32_e32 v233, 0x3fb8aa3b, v233
	v_exp_f32_e32 v226, v226
	v_exp_f32_e32 v227, v227
	v_exp_f32_e32 v228, v228
	v_exp_f32_e32 v229, v229
	v_exp_f32_e32 v230, v230
	v_exp_f32_e32 v231, v231
	v_exp_f32_e32 v232, v232
	v_exp_f32_e32 v233, v233
	v_add_f32_e32 v226, 1.0, v226
	v_add_f32_e32 v227, 1.0, v227
	v_add_f32_e32 v228, 1.0, v228
	v_add_f32_e32 v229, 1.0, v229
	v_add_f32_e32 v230, 1.0, v230
	v_add_f32_e32 v231, 1.0, v231
	v_add_f32_e32 v232, 1.0, v232
	v_add_f32_e32 v233, 1.0, v233
	v_rcp_f32_e32 v226, v226
	v_rcp_f32_e32 v227, v227
	v_rcp_f32_e32 v228, v228
	v_rcp_f32_e32 v229, v229
	v_rcp_f32_e32 v230, v230
	v_rcp_f32_e32 v231, v231
	v_rcp_f32_e32 v232, v232
	v_rcp_f32_e32 v233, v233
	v_fma_f32 v226, -v226, 2.0, 1.0
	v_fma_f32 v227, -v227, 2.0, 1.0
	v_fma_f32 v228, -v228, 2.0, 1.0
	v_fma_f32 v229, -v229, 2.0, 1.0
	v_fma_f32 v230, -v230, 2.0, 1.0
	v_fma_f32 v231, -v231, 2.0, 1.0
	v_fma_f32 v232, -v232, 2.0, 1.0
	v_fma_f32 v233, -v233, 2.0, 1.0
	v_cvt_pk_bf16_f32 v226, v226, v227
	v_cvt_pk_bf16_f32 v227, v228, v229
	v_cvt_pk_bf16_f32 v228, v230, v231
	v_cvt_pk_bf16_f32 v229, v232, v233
	ds_write_b128 v198, v[226:229] offset:49152
	s_waitcnt vmcnt(0)
	v_lshlrev_b32_e32 v108, 16, v48
	v_and_b32_e32 v109, 0xffff0000, v48
	v_lshlrev_b32_e32 v110, 16, v49
	v_and_b32_e32 v111, 0xffff0000, v49
	v_lshlrev_b32_e32 v112, 16, v68
	v_and_b32_e32 v113, 0xffff0000, v68
	v_lshlrev_b32_e32 v250, 16, v69
	v_and_b32_e32 v251, 0xffff0000, v69
	v_lshlrev_b32_e32 v252, 16, v50
	v_and_b32_e32 v253, 0xffff0000, v50
	v_lshlrev_b32_e32 v254, 16, v51
	v_and_b32_e32 v255, 0xffff0000, v51
	v_lshlrev_b32_e32 v222, 16, v70
	v_and_b32_e32 v223, 0xffff0000, v70
	v_lshlrev_b32_e32 v48, 16, v71
	v_and_b32_e32 v49, 0xffff0000, v71
	v_pk_add_f32 v[112:113], v[112:113], v[108:109] neg_lo:[0,1] neg_hi:[0,1]
	v_pk_add_f32 v[250:251], v[250:251], v[110:111] neg_lo:[0,1] neg_hi:[0,1]
	v_pk_add_f32 v[222:223], v[222:223], v[252:253] neg_lo:[0,1] neg_hi:[0,1]
	v_pk_add_f32 v[48:49], v[48:49], v[254:255] neg_lo:[0,1] neg_hi:[0,1]
	v_pk_fma_f32 v[214:215], v[214:215], v[112:113], v[108:109]
	v_pk_fma_f32 v[216:217], v[216:217], v[250:251], v[110:111]
	v_pk_fma_f32 v[218:219], v[218:219], v[222:223], v[252:253]
	v_pk_fma_f32 v[220:221], v[220:221], v[48:49], v[254:255]
	v_cvt_pk_bf16_f32 v214, v214, v215
	v_cvt_pk_bf16_f32 v215, v216, v217
	v_cvt_pk_bf16_f32 v216, v218, v219
	v_cvt_pk_bf16_f32 v217, v220, v221
	ds_write_b128 v198, v[214:217] offset:58368
	v_mov_b32_e32 v69, v73
	v_readlane_b32 s24, v249, 37
	s_ashr_i32 s29, s28, 31
	v_readlane_b32 s30, v249, 50
	v_mov_b32_e32 v72, v73
	s_waitcnt lgkmcnt(0)
	s_barrier
; #define LAS __attribute__((address_space(3)))
; __device__ __forceinline__ float sigmoidf_(float x) { return __builtin_amdgcn_rcpf(1.f + __expf(-x)); }
; #define LBAR() asm volatile("s_waitcnt lgkmcnt(0)\n\ts_barrier" ::: "memory")
; #define MFMA16(a, b, c) __builtin_amdgcn_mfma_f32_16x16x32_bf16(a, b, c, 0, 0, 0)
; __device__ __forceinline__ void chunkA_item(const Args& A, LAS unsigned char* lds, int tid, int lane, int wave, int ci, int ci_next, HeadConstA& H) {
;     ...
;     {
;         const int mt = wave & 3, nth = wave >> 2;
;         bf16x8 ath[2], aad[2];
; #pragma unroll
;         for (int ks = 0; ks < 2; ++ks) { ath[ks] = ldsfrag(lds + CA_TH, mt * 16 + fr, ks * 32 + q4 * 8); aad[ks] = ldsfrag(lds + CA_AD, mt * 16 + fr, ks * 32 + q4 * 8); }
; #pragma unroll
;         for (int nn = 0; nn < 2; ++nn) {
;             const int cl = (nth * 2 + nn) * 16 + fr;
;             f32x4 accw = {0.f, 0.f, 0.f, 0.f}, acca = {0.f, 0.f, 0.f, 0.f};
; #pragma unroll
;             for (int ks = 0; ks < 2; ++ks) { accw = MFMA16(ath[ks], H.bw[nn][ks], accw); acca = MFMA16(aad[ks], H.ba[nn][ks], acca); }
;             const float w0c = H.w0c[nn], a0c = H.a0c[nn];
; #pragma unroll
;             for (int jj = 0; jj < 4; ++jj) { const int t = mt * 16 + q4 * 4 + jj;
;                 ((LAS float*)(lds + CA_LW))[t * 64 + cl] = -0.6065306597126334f * sigmoidf_(w0c + accw[jj]);
;                 ((LAS float*)(lds + CA_AA))[t * 64 + cl] = sigmoidf_(a0c + acca[jj]); }
;         }
;     }
;     LBAR();
;     {
;         const int cc = lane, seg = wave;
;         float lwv[8], pre[8], zr[8], zk[8], zv[8], av[8];
; #pragma unroll
;         for (int i = 0; i < 8; ++i) { const int t = seg * 8 + i; lwv[i] = ((LAS float*)(lds + CA_LW))[t * 64 + cc]; zr[i] = ((LAS float*)(lds + CA_ZR))[t * 64 + cc];
;             zk[i] = ((LAS float*)(lds + CA_ZK))[t * 64 + cc]; zv[i] = ((LAS float*)(lds + CA_ZV))[t * 64 + cc]; av[i] = ((LAS float*)(lds + CA_AA))[t * 64 + cc]; }
;         pre[0] = lwv[0];
; #pragma unroll
;         for (int i = 1; i < 8; ++i) pre[i] = pre[i - 1] + lwv[i];
;         ((LAS float*)(lds + CA_SEG))[seg * 64 + cc] = pre[7];
	ds_read_b128 v[32:35], v199 offset:49152
	ds_read_b128 v[36:39], v199 offset:49216
	ds_read_b128 v[44:47], v199 offset:58368
	ds_read_b128 v[48:51], v199 offset:58432
	s_waitcnt lgkmcnt(3)
	v_mfma_f32_16x16x32_bf16 v[40:43], v[32:35], v[0:3], 0
	v_mfma_f32_16x16x32_bf16 v[32:35], v[32:35], v[16:19], 0
	s_waitcnt lgkmcnt(1)
	v_mfma_f32_16x16x32_bf16 v[52:55], v[44:47], v[8:11], 0
	v_mfma_f32_16x16x32_bf16 v[40:43], v[36:39], v[4:7], v[40:43]
	v_mfma_f32_16x16x32_bf16 v[32:35], v[36:39], v[20:23], v[32:35]
	v_mfma_f32_16x16x32_bf16 v[44:47], v[44:47], v[24:27], 0
	s_nop 5
	v_add_f32_e32 v40, v203, v40
	v_add_f32_e32 v32, v208, v32
	v_add_f32_e32 v41, v203, v41
	s_waitcnt lgkmcnt(0)
	v_mfma_f32_16x16x32_bf16 v[52:55], v[48:51], v[12:15], v[52:55]
	v_add_f32_e32 v42, v203, v42
	v_add_f32_e32 v43, v203, v43
	v_add_f32_e32 v33, v208, v33
	v_mfma_f32_16x16x32_bf16 v[36:39], v[48:51], v[28:31], v[44:47]
	v_mul_f32_e32 v40, 0xbfb8aa3b, v40
	v_mul_f32_e32 v32, 0xbfb8aa3b, v32
	v_mul_f32_e32 v41, 0xbfb8aa3b, v41
	s_nop 0
	v_add_f32_e32 v44, v209, v52
	v_mul_f32_e32 v44, 0xbfb8aa3b, v44
	v_mul_f32_e32 v42, 0xbfb8aa3b, v42
	v_mul_f32_e32 v43, 0xbfb8aa3b, v43
	v_mul_f32_e32 v33, 0xbfb8aa3b, v33
	v_exp_f32_e32 v40, v40
	v_exp_f32_e32 v32, v32
	v_add_f32_e32 v45, v209, v53
	v_exp_f32_e32 v44, v44
	v_exp_f32_e32 v41, v41
	v_exp_f32_e32 v42, v42
	v_exp_f32_e32 v43, v43
	v_exp_f32_e32 v33, v33
	v_mul_f32_e32 v45, 0xbfb8aa3b, v45
	v_add_f32_e32 v46, v209, v54
	v_add_f32_e32 v47, v209, v55
	v_add_f32_e32 v36, v210, v36
	v_exp_f32_e32 v45, v45
	v_mul_f32_e32 v46, 0xbfb8aa3b, v46
	v_mul_f32_e32 v47, 0xbfb8aa3b, v47
	v_mul_f32_e32 v36, 0xbfb8aa3b, v36
	v_add_f32_e32 v40, 1.0, v40
	v_add_f32_e32 v32, 1.0, v32
	v_exp_f32_e32 v46, v46
	v_exp_f32_e32 v47, v47
	v_exp_f32_e32 v36, v36
	v_add_f32_e32 v44, 1.0, v44
	v_add_f32_e32 v41, 1.0, v41
	v_add_f32_e32 v42, 1.0, v42
	v_add_f32_e32 v43, 1.0, v43
	v_add_f32_e32 v33, 1.0, v33
	v_rcp_f32_e32 v40, v40
	v_rcp_f32_e32 v32, v32
	v_rcp_f32_e32 v44, v44
	v_rcp_f32_e32 v41, v41
	v_rcp_f32_e32 v42, v42
	v_rcp_f32_e32 v43, v43
	v_rcp_f32_e32 v33, v33
	v_add_f32_e32 v45, 1.0, v45
	v_rcp_f32_e32 v45, v45
	v_add_f32_e32 v46, 1.0, v46
	v_add_f32_e32 v47, 1.0, v47
	v_add_f32_e32 v36, 1.0, v36
	v_mul_f32_e32 v40, 0xbf1b4598, v40
	v_mul_f32_e32 v32, 0xbf1b4598, v32
	v_rcp_f32_e32 v46, v46
	v_rcp_f32_e32 v47, v47
	v_rcp_f32_e32 v36, v36
	ds_write_b32 v115, v44
	v_mul_f32_e32 v41, 0xbf1b4598, v41
	v_mul_f32_e32 v42, 0xbf1b4598, v42
	v_mul_f32_e32 v43, 0xbf1b4598, v43
	ds_write_b32 v114, v40
	ds_write_b32 v116, v41
	ds_write_b32 v117, v45
	ds_write_b32 v118, v42
	ds_write_b32 v119, v46
	ds_write_b32 v120, v43
	ds_write_b32 v121, v47
	ds_write_b32 v122, v32
	ds_write_b32 v123, v36
	v_mul_f32_e32 v32, 0xbf1b4598, v33
	v_add_f32_e32 v33, v210, v37
	v_add_f32_e32 v34, v208, v34
	v_mul_f32_e32 v33, 0xbfb8aa3b, v33
	v_mul_f32_e32 v34, 0xbfb8aa3b, v34
	v_exp_f32_e32 v33, v33
	v_exp_f32_e32 v34, v34
	ds_write_b32 v124, v32
	v_add_f32_e32 v32, 1.0, v33
	v_add_f32_e32 v33, 1.0, v34
	v_rcp_f32_e32 v32, v32
	v_rcp_f32_e32 v33, v33
	v_add_f32_e32 v34, v210, v38
	v_mul_f32_e32 v34, 0xbfb8aa3b, v34
	v_exp_f32_e32 v34, v34
	ds_write_b32 v125, v32
	v_mul_f32_e32 v32, 0xbf1b4598, v33
	v_add_f32_e32 v33, v208, v35
	v_mul_f32_e32 v33, 0xbfb8aa3b, v33
	ds_write_b32 v126, v32
	v_add_f32_e32 v32, 1.0, v34
	v_exp_f32_e32 v33, v33
	v_add_f32_e32 v34, v210, v39
	v_mul_f32_e32 v34, 0xbfb8aa3b, v34
	v_exp_f32_e32 v34, v34
	v_add_f32_e32 v33, 1.0, v33
	v_rcp_f32_e32 v32, v32
	v_rcp_f32_e32 v33, v33
	v_add_f32_e32 v34, 1.0, v34
	v_rcp_f32_e32 v34, v34
	ds_write_b32 v127, v32
	v_mul_f32_e32 v32, 0xbf1b4598, v33
	ds_write_b32 v135, v32
	ds_write_b32 v139, v34
	s_waitcnt lgkmcnt(0)
	s_barrier
	v_readlane_b32 s24, v249, 3
	ds_read2st64_b32 v[226:227], v141 offset0:0 offset1:1
	ds_read2st64_b32 v[228:229], v141 offset0:2 offset1:3
	ds_read2st64_b32 v[230:231], v141 offset0:4 offset1:5
	ds_read2st64_b32 v[232:233], v141 offset0:6 offset1:7
	ds_read2st64_b32 v[48:49], v143 offset0:64 offset1:65
	ds_read2st64_b32 v[50:51], v143 offset0:66 offset1:67
	ds_read2st64_b32 v[52:53], v143 offset0:68 offset1:69
	ds_read2st64_b32 v[54:55], v143 offset0:70 offset1:71
	ds_read2st64_b32 v[40:41], v141 offset0:64 offset1:65
	ds_read2st64_b32 v[42:43], v141 offset0:66 offset1:67
	ds_read2st64_b32 v[44:45], v141 offset0:68 offset1:69
	ds_read2st64_b32 v[46:47], v141 offset0:70 offset1:71
	ds_read2st64_b32 v[64:65], v143 offset0:0 offset1:1
	ds_read2st64_b32 v[66:67], v143 offset0:2 offset1:3
	ds_read2st64_b32 v[68:69], v143 offset0:4 offset1:5
	ds_read2st64_b32 v[70:71], v143 offset0:6 offset1:7
	ds_read2st64_b32 v[56:57], v143 offset0:128 offset1:129
	ds_read2st64_b32 v[58:59], v143 offset0:130 offset1:131
	ds_read2st64_b32 v[60:61], v143 offset0:132 offset1:133
	ds_read2st64_b32 v[62:63], v143 offset0:134 offset1:135
	v_readlane_b32 s25, v249, 37
	v_readlane_b32 s78, v249, 50
	v_readlane_b32 s79, v249, 51
	s_lshl_b32 s40, s28, 8
	s_add_u32 s78, s78, s40
	s_addc_u32 s79, s79, 0
	v_add_u32_e32 v107, s25, v79
	s_mul_i32 s25, s24, 0x480
	v_add_u32_e32 v103, s25, v164
	s_lshl_b32 s25, s3, 2
	v_mov_b32_e32 v105, s25
	s_mov_b32 s100, 0
	s_brev_b32 s101, 1
	s_waitcnt lgkmcnt(12)
	v_mov_b32_e32 v214, v226
	v_add_f32_e32 v215, v214, v227
	v_add_f32_e32 v216, v215, v228
	v_add_f32_e32 v217, v216, v229
	v_add_f32_e32 v218, v217, v230
	v_add_f32_e32 v219, v218, v231
	v_add_f32_e32 v220, v219, v232
	v_add_f32_e32 v221, v220, v233
	ds_write_b32 v107, v221
	s_waitcnt lgkmcnt(13)
; __device__ __forceinline__ void chunkA_item(const Args& A, LAS unsigned char* lds, int tid, int lane, int wave, int ci, int ci_next, HeadConstA& H) {
;     ...
;         const float kkc = H.kkc, kac = H.kac, rkc = H.rkc;
;         float rhs8[8], nbh8[8], kh8[8];
;         float* BCg = (float*)(A.ws + WS_BC) + (size_t)ci * 64;
; #pragma unroll
;         for (int i = 0; i < 8; ++i) { const int t = seg * 8 + i;
;             const float lg = off + pre[i], lgp = lg - lwv[i];
;             const float kkraw = zk[i] * kkc; const float n2 = wsum_fast(kkraw * kkraw); const float kk = kkraw * __builtin_amdgcn_rsqf(fmaxf(n2, 1e-24f));
;             const float a = av[i], bb = kk * a, km = zk[i] * (1.f + (a - 1.f) * kac);
	v_mul_f32_e32 v32, v211, v48
	v_mul_f32_e32 v33, v211, v49
	v_mul_f32_e32 v34, v211, v50
	v_mul_f32_e32 v35, v211, v51
	v_mul_f32_e32 v36, v211, v52
	v_mul_f32_e32 v37, v211, v53
	v_mul_f32_e32 v38, v211, v54
	v_mul_f32_e32 v39, v211, v55
	v_mul_f32_e32 v108, v32, v32
	v_mul_f32_e32 v109, v33, v33
	v_mul_f32_e32 v110, v34, v34
	v_mul_f32_e32 v111, v35, v35
	v_mul_f32_e32 v112, v36, v36
	v_mul_f32_e32 v113, v37, v37
	v_mul_f32_e32 v250, v38, v38
	v_mul_f32_e32 v251, v39, v39
	v_add_f32_dpp v108, v108, v108 quad_perm:[1,0,3,2] row_mask:0xf bank_mask:0xf
	v_add_f32_dpp v109, v109, v109 quad_perm:[1,0,3,2] row_mask:0xf bank_mask:0xf
	v_add_f32_dpp v110, v110, v110 quad_perm:[1,0,3,2] row_mask:0xf bank_mask:0xf
	v_add_f32_dpp v111, v111, v111 quad_perm:[1,0,3,2] row_mask:0xf bank_mask:0xf
	v_add_f32_dpp v112, v112, v112 quad_perm:[1,0,3,2] row_mask:0xf bank_mask:0xf
	v_add_f32_dpp v113, v113, v113 quad_perm:[1,0,3,2] row_mask:0xf bank_mask:0xf
	v_add_f32_dpp v250, v250, v250 quad_perm:[1,0,3,2] row_mask:0xf bank_mask:0xf
	v_add_f32_dpp v251, v251, v251 quad_perm:[1,0,3,2] row_mask:0xf bank_mask:0xf
	v_add_f32_dpp v108, v108, v108 quad_perm:[2,3,0,1] row_mask:0xf bank_mask:0xf
	v_add_f32_dpp v109, v109, v109 quad_perm:[2,3,0,1] row_mask:0xf bank_mask:0xf
	v_add_f32_dpp v110, v110, v110 quad_perm:[2,3,0,1] row_mask:0xf bank_mask:0xf
	v_add_f32_dpp v111, v111, v111 quad_perm:[2,3,0,1] row_mask:0xf bank_mask:0xf
	v_add_f32_dpp v112, v112, v112 quad_perm:[2,3,0,1] row_mask:0xf bank_mask:0xf
	v_add_f32_dpp v113, v113, v113 quad_perm:[2,3,0,1] row_mask:0xf bank_mask:0xf
	v_add_f32_dpp v250, v250, v250 quad_perm:[2,3,0,1] row_mask:0xf bank_mask:0xf
	v_add_f32_dpp v251, v251, v251 quad_perm:[2,3,0,1] row_mask:0xf bank_mask:0xf
	v_add_f32_dpp v108, v108, v108 row_half_mirror row_mask:0xf bank_mask:0xf
	v_add_f32_dpp v109, v109, v109 row_half_mirror row_mask:0xf bank_mask:0xf
	v_add_f32_dpp v110, v110, v110 row_half_mirror row_mask:0xf bank_mask:0xf
	v_add_f32_dpp v111, v111, v111 row_half_mirror row_mask:0xf bank_mask:0xf
	v_add_f32_dpp v112, v112, v112 row_half_mirror row_mask:0xf bank_mask:0xf
	v_add_f32_dpp v113, v113, v113 row_half_mirror row_mask:0xf bank_mask:0xf
	v_add_f32_dpp v250, v250, v250 row_half_mirror row_mask:0xf bank_mask:0xf
	v_add_f32_dpp v251, v251, v251 row_half_mirror row_mask:0xf bank_mask:0xf
	v_add_f32_dpp v108, v108, v108 row_mirror row_mask:0xf bank_mask:0xf
	v_add_f32_dpp v109, v109, v109 row_mirror row_mask:0xf bank_mask:0xf
	v_add_f32_dpp v110, v110, v110 row_mirror row_mask:0xf bank_mask:0xf
	v_add_f32_dpp v111, v111, v111 row_mirror row_mask:0xf bank_mask:0xf
	v_add_f32_dpp v112, v112, v112 row_mirror row_mask:0xf bank_mask:0xf
	v_add_f32_dpp v113, v113, v113 row_mirror row_mask:0xf bank_mask:0xf
	v_add_f32_dpp v250, v250, v250 row_mirror row_mask:0xf bank_mask:0xf
	v_add_f32_dpp v251, v251, v251 row_mirror row_mask:0xf bank_mask:0xf
	v_add_f32_dpp v108, v108, v108 row_bcast:15 row_mask:0xa bank_mask:0xf
	v_add_f32_dpp v109, v109, v109 row_bcast:15 row_mask:0xa bank_mask:0xf
	v_add_f32_dpp v110, v110, v110 row_bcast:15 row_mask:0xa bank_mask:0xf
	v_add_f32_dpp v111, v111, v111 row_bcast:15 row_mask:0xa bank_mask:0xf
	v_add_f32_dpp v112, v112, v112 row_bcast:15 row_mask:0xa bank_mask:0xf
	v_add_f32_dpp v113, v113, v113 row_bcast:15 row_mask:0xa bank_mask:0xf
	v_add_f32_dpp v250, v250, v250 row_bcast:15 row_mask:0xa bank_mask:0xf
	v_add_f32_dpp v251, v251, v251 row_bcast:15 row_mask:0xa bank_mask:0xf
	v_add_f32_dpp v108, v108, v108 row_bcast:31 row_mask:0xc bank_mask:0xf
	v_add_f32_dpp v109, v109, v109 row_bcast:31 row_mask:0xc bank_mask:0xf
	v_add_f32_dpp v110, v110, v110 row_bcast:31 row_mask:0xc bank_mask:0xf
	v_add_f32_dpp v111, v111, v111 row_bcast:31 row_mask:0xc bank_mask:0xf
	v_add_f32_dpp v112, v112, v112 row_bcast:31 row_mask:0xc bank_mask:0xf
	v_add_f32_dpp v113, v113, v113 row_bcast:31 row_mask:0xc bank_mask:0xf
	v_add_f32_dpp v250, v250, v250 row_bcast:31 row_mask:0xc bank_mask:0xf
	v_add_f32_dpp v251, v251, v251 row_bcast:31 row_mask:0xc bank_mask:0xf
	v_readlane_b32 s30, v108, 63
	v_readlane_b32 s31, v109, 63
	v_readlane_b32 s34, v110, 63
	v_readlane_b32 s35, v111, 63
	v_readlane_b32 s36, v112, 63
	v_readlane_b32 s37, v113, 63
	v_readlane_b32 s38, v250, 63
	v_readlane_b32 s39, v251, 63
	s_waitcnt lgkmcnt(9)
	v_add_f32_e32 v108, -1.0, v40
	v_add_f32_e32 v109, -1.0, v41
	v_add_f32_e32 v110, -1.0, v42
	v_add_f32_e32 v111, -1.0, v43
	v_add_f32_e32 v112, -1.0, v44
	v_add_f32_e32 v113, -1.0, v45
	v_add_f32_e32 v250, -1.0, v46
	v_add_f32_e32 v251, -1.0, v47
	v_fma_f32 v108, v212, v108, 1.0
	v_fma_f32 v109, v212, v109, 1.0
	v_fma_f32 v110, v212, v110, 1.0
	v_fma_f32 v111, v212, v111, 1.0
	v_fma_f32 v112, v212, v112, 1.0
	v_fma_f32 v113, v212, v113, 1.0
	v_fma_f32 v250, v212, v250, 1.0
	v_fma_f32 v251, v212, v251, 1.0
	v_mul_f32_e32 v48, v48, v108
	v_mul_f32_e32 v49, v49, v109
	v_mul_f32_e32 v50, v50, v110
	v_mul_f32_e32 v51, v51, v111
	v_mul_f32_e32 v52, v52, v112
	v_mul_f32_e32 v53, v53, v113
	v_mul_f32_e32 v54, v54, v250
	v_mul_f32_e32 v55, v55, v251
	v_mov_b32_e32 v108, s30
	v_mov_b32_e32 v109, s31
	v_mov_b32_e32 v110, s34
	v_mov_b32_e32 v111, s35
	v_mov_b32_e32 v112, s36
	v_mov_b32_e32 v113, s37
	v_mov_b32_e32 v250, s38
	v_mov_b32_e32 v251, s39
	v_max_f32_e32 v108, 0x179abe15, v108
	v_max_f32_e32 v109, 0x179abe15, v109
	v_max_f32_e32 v110, 0x179abe15, v110
	v_max_f32_e32 v111, 0x179abe15, v111
	v_max_f32_e32 v112, 0x179abe15, v112
	v_max_f32_e32 v113, 0x179abe15, v113
	v_max_f32_e32 v250, 0x179abe15, v250
	v_max_f32_e32 v251, 0x179abe15, v251
	v_rsq_f32_e32 v108, v108
	v_rsq_f32_e32 v109, v109
	v_rsq_f32_e32 v110, v110
	v_rsq_f32_e32 v111, v111
	v_rsq_f32_e32 v112, v112
	v_rsq_f32_e32 v113, v113
	v_rsq_f32_e32 v250, v250
	v_rsq_f32_e32 v251, v251
	v_mul_f32_e32 v32, v32, v108
	v_mul_f32_e32 v33, v33, v109
	v_mul_f32_e32 v34, v34, v110
	v_mul_f32_e32 v35, v35, v111
	v_mul_f32_e32 v36, v36, v112
	v_mul_f32_e32 v37, v37, v113
	v_mul_f32_e32 v38, v38, v250
	v_mul_f32_e32 v39, v39, v251
	v_mul_f32_e32 v40, v40, v32
	v_mul_f32_e32 v41, v41, v33
	v_mul_f32_e32 v42, v42, v34
	v_mul_f32_e32 v43, v43, v35
	v_mul_f32_e32 v44, v44, v36
	v_mul_f32_e32 v45, v45, v37
	v_mul_f32_e32 v46, v46, v38
	v_mul_f32_e32 v47, v47, v39
	s_waitcnt lgkmcnt(5)
; __device__ __forceinline__ void chunkA_item(const Args& A, LAS unsigned char* lds, int tid, int lane, int wave, int ci, int ci_next, HeadConstA& H) {
;     ...
;             const float kkraw = zk[i] * kkc; const float n2 = wsum_fast(kkraw * kkraw); const float kk = kkraw * __builtin_amdgcn_rsqf(fmaxf(n2, 1e-24f));
;             const float a = av[i], bb = kk * a, km = zk[i] * (1.f + (a - 1.f) * kac);
;             const float bc = wsum_fast(zr[i] * km * rkc); if (lane == 0) BCg[t] = bc;
	v_mul_f32_e32 v108, v64, v48
	v_mul_f32_e32 v109, v65, v49
	v_mul_f32_e32 v110, v66, v50
	v_mul_f32_e32 v111, v67, v51
	v_mul_f32_e32 v112, v68, v52
	v_mul_f32_e32 v113, v69, v53
	v_mul_f32_e32 v250, v70, v54
	v_mul_f32_e32 v251, v71, v55
	v_mul_f32_e32 v108, v213, v108
	v_mul_f32_e32 v109, v213, v109
	v_mul_f32_e32 v110, v213, v110
	v_mul_f32_e32 v111, v213, v111
	v_mul_f32_e32 v112, v213, v112
	v_mul_f32_e32 v113, v213, v113
	v_mul_f32_e32 v250, v213, v250
	v_mul_f32_e32 v251, v213, v251
	v_add_f32_dpp v108, v108, v108 quad_perm:[1,0,3,2] row_mask:0xf bank_mask:0xf
	v_add_f32_dpp v109, v109, v109 quad_perm:[1,0,3,2] row_mask:0xf bank_mask:0xf
	v_add_f32_dpp v110, v110, v110 quad_perm:[1,0,3,2] row_mask:0xf bank_mask:0xf
	v_add_f32_dpp v111, v111, v111 quad_perm:[1,0,3,2] row_mask:0xf bank_mask:0xf
	v_add_f32_dpp v112, v112, v112 quad_perm:[1,0,3,2] row_mask:0xf bank_mask:0xf
	v_add_f32_dpp v113, v113, v113 quad_perm:[1,0,3,2] row_mask:0xf bank_mask:0xf
	v_add_f32_dpp v250, v250, v250 quad_perm:[1,0,3,2] row_mask:0xf bank_mask:0xf
	v_add_f32_dpp v251, v251, v251 quad_perm:[1,0,3,2] row_mask:0xf bank_mask:0xf
	v_add_f32_dpp v108, v108, v108 quad_perm:[2,3,0,1] row_mask:0xf bank_mask:0xf
	v_add_f32_dpp v109, v109, v109 quad_perm:[2,3,0,1] row_mask:0xf bank_mask:0xf
	v_add_f32_dpp v110, v110, v110 quad_perm:[2,3,0,1] row_mask:0xf bank_mask:0xf
	v_add_f32_dpp v111, v111, v111 quad_perm:[2,3,0,1] row_mask:0xf bank_mask:0xf
	v_add_f32_dpp v112, v112, v112 quad_perm:[2,3,0,1] row_mask:0xf bank_mask:0xf
	v_add_f32_dpp v113, v113, v113 quad_perm:[2,3,0,1] row_mask:0xf bank_mask:0xf
	v_add_f32_dpp v250, v250, v250 quad_perm:[2,3,0,1] row_mask:0xf bank_mask:0xf
	v_add_f32_dpp v251, v251, v251 quad_perm:[2,3,0,1] row_mask:0xf bank_mask:0xf
	v_add_f32_dpp v108, v108, v108 row_half_mirror row_mask:0xf bank_mask:0xf
	v_add_f32_dpp v109, v109, v109 row_half_mirror row_mask:0xf bank_mask:0xf
	v_add_f32_dpp v110, v110, v110 row_half_mirror row_mask:0xf bank_mask:0xf
	v_add_f32_dpp v111, v111, v111 row_half_mirror row_mask:0xf bank_mask:0xf
	v_add_f32_dpp v112, v112, v112 row_half_mirror row_mask:0xf bank_mask:0xf
	v_add_f32_dpp v113, v113, v113 row_half_mirror row_mask:0xf bank_mask:0xf
	v_add_f32_dpp v250, v250, v250 row_half_mirror row_mask:0xf bank_mask:0xf
	v_add_f32_dpp v251, v251, v251 row_half_mirror row_mask:0xf bank_mask:0xf
	v_add_f32_dpp v108, v108, v108 row_mirror row_mask:0xf bank_mask:0xf
	v_add_f32_dpp v109, v109, v109 row_mirror row_mask:0xf bank_mask:0xf
	v_add_f32_dpp v110, v110, v110 row_mirror row_mask:0xf bank_mask:0xf
	v_add_f32_dpp v111, v111, v111 row_mirror row_mask:0xf bank_mask:0xf
	v_add_f32_dpp v112, v112, v112 row_mirror row_mask:0xf bank_mask:0xf
	v_add_f32_dpp v113, v113, v113 row_mirror row_mask:0xf bank_mask:0xf
	v_add_f32_dpp v250, v250, v250 row_mirror row_mask:0xf bank_mask:0xf
	v_add_f32_dpp v251, v251, v251 row_mirror row_mask:0xf bank_mask:0xf
	v_add_f32_dpp v108, v108, v108 row_bcast:15 row_mask:0xa bank_mask:0xf
	v_add_f32_dpp v109, v109, v109 row_bcast:15 row_mask:0xa bank_mask:0xf
	v_add_f32_dpp v110, v110, v110 row_bcast:15 row_mask:0xa bank_mask:0xf
	v_add_f32_dpp v111, v111, v111 row_bcast:15 row_mask:0xa bank_mask:0xf
	v_add_f32_dpp v112, v112, v112 row_bcast:15 row_mask:0xa bank_mask:0xf
	v_add_f32_dpp v113, v113, v113 row_bcast:15 row_mask:0xa bank_mask:0xf
	v_add_f32_dpp v250, v250, v250 row_bcast:15 row_mask:0xa bank_mask:0xf
	v_add_f32_dpp v251, v251, v251 row_bcast:15 row_mask:0xa bank_mask:0xf
	v_add_f32_dpp v108, v108, v108 row_bcast:31 row_mask:0xc bank_mask:0xf
	v_add_f32_dpp v109, v109, v109 row_bcast:31 row_mask:0xc bank_mask:0xf
	v_add_f32_dpp v110, v110, v110 row_bcast:31 row_mask:0xc bank_mask:0xf
	v_add_f32_dpp v111, v111, v111 row_bcast:31 row_mask:0xc bank_mask:0xf
	v_add_f32_dpp v112, v112, v112 row_bcast:31 row_mask:0xc bank_mask:0xf
	v_add_f32_dpp v113, v113, v113 row_bcast:31 row_mask:0xc bank_mask:0xf
	v_add_f32_dpp v250, v250, v250 row_bcast:31 row_mask:0xc bank_mask:0xf
	v_add_f32_dpp v251, v251, v251 row_bcast:31 row_mask:0xc bank_mask:0xf
	s_mov_b64 exec, s[100:101]
	global_store_dword v105, v108, s[78:79]
	global_store_dword v105, v109, s[78:79] offset:4
	global_store_dword v105, v110, s[78:79] offset:8
	global_store_dword v105, v111, s[78:79] offset:12
	global_store_dword v105, v112, s[78:79] offset:16
	global_store_dword v105, v113, s[78:79] offset:20
	global_store_dword v105, v250, s[78:79] offset:24
	global_store_dword v105, v251, s[78:79] offset:28
	s_mov_b64 exec, -1
	s_waitcnt lgkmcnt(0)
	s_barrier
; #define LAS __attribute__((address_space(3)))
; __device__ __forceinline__ unsigned f2bf(float f) { return pk2(f, 0.f) & 0xffffu; }
; #define LBAR() asm volatile("s_waitcnt lgkmcnt(0)\n\ts_barrier" ::: "memory")
; __device__ __forceinline__ void chunkA_item(const Args& A, LAS unsigned char* lds, int tid, int lane, int wave, int ci, int ci_next, HeadConstA& H) {
;     ...
;         LBAR();
;         float off = 0.f, tot = 0.f;
; #pragma unroll
;         for (int s = 0; s < 8; ++s) { const float v = ((LAS float*)(lds + CA_SEG))[s * 64 + cc]; tot += v; if (s < seg) off += v; }
;         const float kkc = H.kkc, kac = H.kac, rkc = H.rkc;
;         float rhs8[8], nbh8[8], kh8[8];
;         float* BCg = (float*)(A.ws + WS_BC) + (size_t)ci * 64;
; #pragma unroll
;         for (int i = 0; i < 8; ++i) { const int t = seg * 8 + i;
;             const float lg = off + pre[i], lgp = lg - lwv[i];
;             const float kkraw = zk[i] * kkc; const float n2 = wsum_fast(kkraw * kkraw); const float kk = kkraw * __builtin_amdgcn_rsqf(fmaxf(n2, 1e-24f));
;             const float a = av[i], bb = kk * a, km = zk[i] * (1.f + (a - 1.f) * kac);
;             const float bc = wsum_fast(zr[i] * km * rkc); if (lane == 0) BCg[t] = bc;
;             const float e_in = __expf(lg), e_pr = __expf(lgp), e_out = __expf(-lg), e_h = __expf(tot - lg);
;             const float kkt = kk * e_pr; rhs8[i] = kkt; nbh8[i] = -(bb * e_h); kh8[i] = km * e_h;
;             *(LAS unsigned short*)(lds + CA_KKT + t * 144 + cc * 2) = (unsigned short)f2bf(kkt);
;             *(LAS unsigned short*)(lds + CA_RT + t * 144 + cc * 2) = (unsigned short)f2bf(zr[i] * e_in);
	ds_read2st64_b32 v[108:109], v79 offset0:0 offset1:1
	ds_read2st64_b32 v[110:111], v79 offset0:2 offset1:3
	ds_read2st64_b32 v[112:113], v79 offset0:4 offset1:5
	ds_read2st64_b32 v[250:251], v79 offset0:6 offset1:7
	s_waitcnt lgkmcnt(0)
	v_mov_b32_e32 v72, 0
	v_mov_b32_e32 v222, v108
	s_cmp_gt_u32 s24, 0
	s_cselect_b32 s40, 1.0, 0
	v_fmac_f32_e32 v72, s40, v108
	v_add_f32_e32 v222, v222, v109
	s_cmp_gt_u32 s24, 1
	s_cselect_b32 s40, 1.0, 0
	v_fmac_f32_e32 v72, s40, v109
	v_add_f32_e32 v222, v222, v110
	s_cmp_gt_u32 s24, 2
	s_cselect_b32 s40, 1.0, 0
	v_fmac_f32_e32 v72, s40, v110
	v_add_f32_e32 v222, v222, v111
	s_cmp_gt_u32 s24, 3
	s_cselect_b32 s40, 1.0, 0
	v_fmac_f32_e32 v72, s40, v111
	v_add_f32_e32 v222, v222, v112
	s_cmp_gt_u32 s24, 4
	s_cselect_b32 s40, 1.0, 0
	v_fmac_f32_e32 v72, s40, v112
	v_add_f32_e32 v222, v222, v113
	s_cmp_gt_u32 s24, 5
	s_cselect_b32 s40, 1.0, 0
	v_fmac_f32_e32 v72, s40, v113
	v_add_f32_e32 v222, v222, v250
	s_cmp_gt_u32 s24, 6
	s_cselect_b32 s40, 1.0, 0
	v_fmac_f32_e32 v72, s40, v250
	v_add_f32_e32 v222, v222, v251
	v_add_f32_e32 v214, v72, v214
	v_add_f32_e32 v215, v72, v215
	v_add_f32_e32 v216, v72, v216
	v_add_f32_e32 v217, v72, v217
	v_add_f32_e32 v218, v72, v218
	v_add_f32_e32 v219, v72, v219
	v_add_f32_e32 v220, v72, v220
	v_add_f32_e32 v221, v72, v221
	v_sub_f32_e32 v226, v214, v226
	v_sub_f32_e32 v227, v215, v227
	v_sub_f32_e32 v228, v216, v228
	v_sub_f32_e32 v229, v217, v229
	v_sub_f32_e32 v230, v218, v230
	v_sub_f32_e32 v231, v219, v231
	v_sub_f32_e32 v232, v220, v232
	v_sub_f32_e32 v233, v221, v233
	v_mul_f32_e32 v226, 0x3fb8aa3b, v226
	v_mul_f32_e32 v227, 0x3fb8aa3b, v227
	v_mul_f32_e32 v228, 0x3fb8aa3b, v228
	v_mul_f32_e32 v229, 0x3fb8aa3b, v229
	v_mul_f32_e32 v230, 0x3fb8aa3b, v230
	v_mul_f32_e32 v231, 0x3fb8aa3b, v231
	v_mul_f32_e32 v232, 0x3fb8aa3b, v232
	v_mul_f32_e32 v233, 0x3fb8aa3b, v233
	v_exp_f32_e32 v226, v226
	v_exp_f32_e32 v227, v227
	v_exp_f32_e32 v228, v228
	v_exp_f32_e32 v229, v229
	v_exp_f32_e32 v230, v230
	v_exp_f32_e32 v231, v231
	v_exp_f32_e32 v232, v232
	v_exp_f32_e32 v233, v233
	v_mul_f32_e32 v32, v226, v32
	v_mul_f32_e32 v33, v227, v33
	v_mul_f32_e32 v34, v228, v34
	v_mul_f32_e32 v35, v229, v35
	v_mul_f32_e32 v36, v230, v36
	v_mul_f32_e32 v37, v231, v37
	v_mul_f32_e32 v38, v232, v38
	v_mul_f32_e32 v39, v233, v39
	v_cvt_pk_bf16_f32 v108, v32, v32
	v_cvt_pk_bf16_f32 v109, v33, v33
	v_cvt_pk_bf16_f32 v110, v34, v34
	v_cvt_pk_bf16_f32 v111, v35, v35
	v_cvt_pk_bf16_f32 v112, v36, v36
	v_cvt_pk_bf16_f32 v113, v37, v37
	v_cvt_pk_bf16_f32 v250, v38, v38
	v_cvt_pk_bf16_f32 v251, v39, v39
	ds_write_b16 v103, v108 offset:0
	ds_write_b16 v103, v109 offset:144
	ds_write_b16 v103, v110 offset:288
	ds_write_b16 v103, v111 offset:432
	ds_write_b16 v103, v112 offset:576
	ds_write_b16 v103, v113 offset:720
	ds_write_b16 v103, v250 offset:864
	ds_write_b16 v103, v251 offset:1008
	v_mul_f32_e32 v226, 0x3fb8aa3b, v214
	v_mul_f32_e32 v227, 0x3fb8aa3b, v215
	v_mul_f32_e32 v228, 0x3fb8aa3b, v216
	v_mul_f32_e32 v229, 0x3fb8aa3b, v217
	v_mul_f32_e32 v230, 0x3fb8aa3b, v218
	v_mul_f32_e32 v231, 0x3fb8aa3b, v219
	v_mul_f32_e32 v232, 0x3fb8aa3b, v220
	v_mul_f32_e32 v233, 0x3fb8aa3b, v221
	v_exp_f32_e32 v226, v226
	v_exp_f32_e32 v227, v227
	v_exp_f32_e32 v228, v228
	v_exp_f32_e32 v229, v229
	v_exp_f32_e32 v230, v230
	v_exp_f32_e32 v231, v231
	v_exp_f32_e32 v232, v232
	v_exp_f32_e32 v233, v233
	v_mul_f32_e32 v64, v64, v226
	v_mul_f32_e32 v65, v65, v227
	v_mul_f32_e32 v66, v66, v228
	v_mul_f32_e32 v67, v67, v229
	v_mul_f32_e32 v68, v68, v230
	v_mul_f32_e32 v69, v69, v231
	v_mul_f32_e32 v70, v70, v232
	v_mul_f32_e32 v71, v71, v233
	v_cvt_pk_bf16_f32 v108, v64, v64
	v_cvt_pk_bf16_f32 v109, v65, v65
	v_cvt_pk_bf16_f32 v110, v66, v66
	v_cvt_pk_bf16_f32 v111, v67, v67
	v_cvt_pk_bf16_f32 v112, v68, v68
	v_cvt_pk_bf16_f32 v113, v69, v69
	v_cvt_pk_bf16_f32 v250, v70, v70
	v_cvt_pk_bf16_f32 v251, v71, v71
	ds_write_b16 v103, v108 offset:27648
	ds_write_b16 v103, v109 offset:27792
	ds_write_b16 v103, v110 offset:27936
	ds_write_b16 v103, v111 offset:28080
	ds_write_b16 v103, v112 offset:28224
	ds_write_b16 v103, v113 offset:28368
	ds_write_b16 v103, v250 offset:28512
; #define LAS __attribute__((address_space(3)))
; __device__ __forceinline__ unsigned f2bf(float f) { return pk2(f, 0.f) & 0xffffu; }
; __device__ __forceinline__ u32x4 pack8(const float* f) { u32x4 o; o.x = pk2(f[0], f[1]); o.y = pk2(f[2], f[3]); o.z = pk2(f[4], f[5]); o.w = pk2(f[6], f[7]); return o; }
; __device__ __forceinline__ void chunkA_item(const Args& A, LAS unsigned char* lds, int tid, int lane, int wave, int ci, int ci_next, HeadConstA& H) {
;     ...
;             const float e_in = __expf(lg), e_pr = __expf(lgp), e_out = __expf(-lg), e_h = __expf(tot - lg);
;             const float kkt = kk * e_pr; rhs8[i] = kkt; nbh8[i] = -(bb * e_h); kh8[i] = km * e_h;
;             *(LAS unsigned short*)(lds + CA_KKT + t * 144 + cc * 2) = (unsigned short)f2bf(kkt);
;             *(LAS unsigned short*)(lds + CA_RT + t * 144 + cc * 2) = (unsigned short)f2bf(zr[i] * e_in);
;             *(LAS unsigned short*)(lds + CA_BT + t * 144 + cc * 2) = (unsigned short)f2bf(bb * e_out);
;             *(LAS unsigned short*)(lds + CA_KT + t * 144 + cc * 2) = (unsigned short)f2bf(km * e_out); }
;         *(LAS u32x4*)(lds + CA_NBHT + cc * 144 + seg * 16) = pack8(nbh8); *(LAS u32x4*)(lds + CA_KHT + cc * 144 + seg * 16) = pack8(kh8); *(LAS u32x4*)(lds + CA_VT + cc * 144 + seg * 16) = pack8(zv);
;         LAS f32x4* rp = (LAS f32x4*)(lds + CA_RHS + (cc * 68 + seg * 8) * 4); rp[0] = (f32x4){rhs8[0], rhs8[1], rhs8[2], rhs8[3]}; rp[1] = (f32x4){rhs8[4], rhs8[5], rhs8[6], rhs8[7]};
;         if (seg == 0) ((LAS float*)(lds + CA_G))[cc] = __expf(tot);
	ds_write_b16 v103, v251 offset:28656
	v_mul_f32_e32 v226, 0xbfb8aa3b, v214
	v_mul_f32_e32 v227, 0xbfb8aa3b, v215
	v_mul_f32_e32 v228, 0xbfb8aa3b, v216
	v_mul_f32_e32 v229, 0xbfb8aa3b, v217
	v_mul_f32_e32 v230, 0xbfb8aa3b, v218
	v_mul_f32_e32 v231, 0xbfb8aa3b, v219
	v_mul_f32_e32 v232, 0xbfb8aa3b, v220
	v_mul_f32_e32 v233, 0xbfb8aa3b, v221
	v_exp_f32_e32 v226, v226
	v_exp_f32_e32 v227, v227
	v_exp_f32_e32 v228, v228
	v_exp_f32_e32 v229, v229
	v_exp_f32_e32 v230, v230
	v_exp_f32_e32 v231, v231
	v_exp_f32_e32 v232, v232
	v_exp_f32_e32 v233, v233
	v_mul_f32_e32 v64, v226, v40
	v_mul_f32_e32 v65, v227, v41
	v_mul_f32_e32 v66, v228, v42
	v_mul_f32_e32 v67, v229, v43
	v_mul_f32_e32 v68, v230, v44
	v_mul_f32_e32 v69, v231, v45
	v_mul_f32_e32 v70, v232, v46
	v_mul_f32_e32 v71, v233, v47
	v_cvt_pk_bf16_f32 v108, v64, v64
	v_cvt_pk_bf16_f32 v109, v65, v65
	v_cvt_pk_bf16_f32 v110, v66, v66
	v_cvt_pk_bf16_f32 v111, v67, v67
	v_cvt_pk_bf16_f32 v112, v68, v68
	v_cvt_pk_bf16_f32 v113, v69, v69
	v_cvt_pk_bf16_f32 v250, v70, v70
	v_cvt_pk_bf16_f32 v251, v71, v71
	ds_write_b16 v103, v108 offset:9216
	ds_write_b16 v103, v109 offset:9360
	ds_write_b16 v103, v110 offset:9504
	ds_write_b16 v103, v111 offset:9648
	ds_write_b16 v103, v112 offset:9792
	ds_write_b16 v103, v113 offset:9936
	ds_write_b16 v103, v250 offset:10080
	ds_write_b16 v103, v251 offset:10224
	v_mul_f32_e32 v64, v48, v226
	v_mul_f32_e32 v65, v49, v227
	v_mul_f32_e32 v66, v50, v228
	v_mul_f32_e32 v67, v51, v229
	v_mul_f32_e32 v68, v52, v230
	v_mul_f32_e32 v69, v53, v231
	v_mul_f32_e32 v70, v54, v232
	v_mul_f32_e32 v71, v55, v233
	v_cvt_pk_bf16_f32 v108, v64, v64
	v_cvt_pk_bf16_f32 v109, v65, v65
	v_cvt_pk_bf16_f32 v110, v66, v66
	v_cvt_pk_bf16_f32 v111, v67, v67
	v_cvt_pk_bf16_f32 v112, v68, v68
	v_cvt_pk_bf16_f32 v113, v69, v69
	v_cvt_pk_bf16_f32 v250, v70, v70
	v_cvt_pk_bf16_f32 v251, v71, v71
	ds_write_b16 v103, v108 offset:18432
	ds_write_b16 v103, v109 offset:18576
	ds_write_b16 v103, v110 offset:18720
	ds_write_b16 v103, v111 offset:18864
	ds_write_b16 v103, v112 offset:19008
	ds_write_b16 v103, v113 offset:19152
	ds_write_b16 v103, v250 offset:19296
	ds_write_b16 v103, v251 offset:19440
	v_sub_f32_e32 v226, v222, v214
	v_sub_f32_e32 v227, v222, v215
	v_sub_f32_e32 v228, v222, v216
	v_sub_f32_e32 v229, v222, v217
	v_sub_f32_e32 v230, v222, v218
	v_sub_f32_e32 v231, v222, v219
	v_sub_f32_e32 v232, v222, v220
	v_sub_f32_e32 v233, v222, v221
	v_mul_f32_e32 v226, 0x3fb8aa3b, v226
	v_mul_f32_e32 v227, 0x3fb8aa3b, v227
	v_mul_f32_e32 v228, 0x3fb8aa3b, v228
	v_mul_f32_e32 v229, 0x3fb8aa3b, v229
	v_mul_f32_e32 v230, 0x3fb8aa3b, v230
	v_mul_f32_e32 v231, 0x3fb8aa3b, v231
	v_mul_f32_e32 v232, 0x3fb8aa3b, v232
	v_mul_f32_e32 v233, 0x3fb8aa3b, v233
	v_exp_f32_e32 v226, v226
	v_exp_f32_e32 v227, v227
	v_exp_f32_e32 v228, v228
	v_exp_f32_e32 v229, v229
	v_exp_f32_e32 v230, v230
	v_exp_f32_e32 v231, v231
	v_exp_f32_e32 v232, v232
	v_exp_f32_e32 v233, v233
	v_mul_f32_e64 v40, v40, -v226
	v_mul_f32_e64 v41, v41, -v227
	v_mul_f32_e64 v42, v42, -v228
	v_mul_f32_e64 v43, v43, -v229
	v_mul_f32_e64 v44, v44, -v230
	v_mul_f32_e64 v45, v45, -v231
	v_mul_f32_e64 v46, v46, -v232
	v_mul_f32_e64 v47, v47, -v233
	v_mul_f32_e32 v48, v48, v226
	v_mul_f32_e32 v49, v49, v227
	v_mul_f32_e32 v50, v50, v228
	v_mul_f32_e32 v51, v51, v229
	v_mul_f32_e32 v52, v52, v230
	v_mul_f32_e32 v53, v53, v231
	v_mul_f32_e32 v54, v54, v232
	v_mul_f32_e32 v55, v55, v233
	v_cvt_pk_bf16_f32 v40, v40, v41
	v_cvt_pk_bf16_f32 v41, v42, v43
	v_cvt_pk_bf16_f32 v42, v44, v45
	v_cvt_pk_bf16_f32 v43, v46, v47
	v_cvt_pk_bf16_f32 v48, v48, v49
	v_cvt_pk_bf16_f32 v49, v50, v51
	v_cvt_pk_bf16_f32 v50, v52, v53
	v_cvt_pk_bf16_f32 v51, v54, v55
	v_cvt_pk_bf16_f32 v56, v56, v57
	v_cvt_pk_bf16_f32 v57, v58, v59
	v_cvt_pk_bf16_f32 v58, v60, v61
	v_cvt_pk_bf16_f32 v59, v62, v63
	ds_write_b128 v181, v[40:43] offset:36864
	ds_write_b128 v181, v[48:51] offset:46080
	ds_write_b128 v181, v[56:59] offset:55296
	ds_write_b128 v182, v[32:35] offset:64512
	ds_write_b128 v182, v[36:39] offset:64528
	s_andn2_b64 vcc, exec, s[14:15]
	s_cbranch_vccnz .La3_skip_g
	v_mul_f32_e32 v108, 0x3fb8aa3b, v222
	v_exp_f32_e32 v108, v108
	ds_write_b32 v165, v108

; __global__ void __launch_bounds__(512, 2) hymba_fwd(Args A) {
	.amdhsa_kernel _Z9hymba_fwd4Args
		.amdhsa_group_segment_fixed_size 0
		.amdhsa_private_segment_fixed_size 0
		.amdhsa_kernarg_size 480
		.amdhsa_user_sgpr_count 2
		.amdhsa_user_sgpr_dispatch_ptr 0
		.amdhsa_user_sgpr_queue_ptr 0
		.amdhsa_user_sgpr_kernarg_segment_ptr 1
		.amdhsa_user_sgpr_dispatch_id 0
		.amdhsa_user_sgpr_kernarg_preload_length 0
		.amdhsa_user_sgpr_kernarg_preload_offset 0
		.amdhsa_user_sgpr_private_segment_size 0
		.amdhsa_uses_dynamic_stack 0
		.amdhsa_enable_private_segment 0
		.amdhsa_system_sgpr_workgroup_id_x 1
		.amdhsa_system_sgpr_workgroup_id_y 0
		.amdhsa_system_sgpr_workgroup_id_z 0
		.amdhsa_system_sgpr_workgroup_info 0
		.amdhsa_system_vgpr_workitem_id 2
		.amdhsa_next_free_vgpr 256
		.amdhsa_next_free_sgpr 102
		.amdhsa_accum_offset 256
		.amdhsa_reserve_vcc 1
		.amdhsa_float_round_mode_32 0
		.amdhsa_float_round_mode_16_64 0
		.amdhsa_float_denorm_mode_32 3
		.amdhsa_float_denorm_mode_16_64 3
		.amdhsa_dx10_clamp 1
		.amdhsa_ieee_mode 1
		.amdhsa_fp16_overflow 0
		.amdhsa_tg_split 0
		.amdhsa_exception_fp_ieee_invalid_op 0
		.amdhsa_exception_fp_denorm_src 0
		.amdhsa_exception_fp_ieee_div_zero 0
		.amdhsa_exception_fp_ieee_overflow 0
		.amdhsa_exception_fp_ieee_underflow 0
		.amdhsa_exception_fp_ieee_inexact 0
		.amdhsa_exception_int_div_zero 0
	.end_amdhsa_kernel

; __global__ void __launch_bounds__(512, 2) hymba_fwd(Args A) {
amdhsa.kernels:
  - .agpr_count:     0
    .args:
      - .offset:         0
        .size:           224
        .value_kind:     by_value
      - .offset:         224
        .size:           4
        .value_kind:     hidden_block_count_x
      - .offset:         228
        .size:           4
        .value_kind:     hidden_block_count_y
      - .offset:         232
        .size:           4
        .value_kind:     hidden_block_count_z
      - .offset:         236
        .size:           2
        .value_kind:     hidden_group_size_x
      - .offset:         238
        .size:           2
        .value_kind:     hidden_group_size_y
      - .offset:         240
        .size:           2
        .value_kind:     hidden_group_size_z
      - .offset:         242
        .size:           2
        .value_kind:     hidden_remainder_x
      - .offset:         244
        .size:           2
        .value_kind:     hidden_remainder_y
      - .offset:         246
        .size:           2
        .value_kind:     hidden_remainder_z
      - .offset:         264
        .size:           8
        .value_kind:     hidden_global_offset_x
      - .offset:         272
        .size:           8
        .value_kind:     hidden_global_offset_y
      - .offset:         280
        .size:           8
        .value_kind:     hidden_global_offset_z
      - .offset:         288
        .size:           2
        .value_kind:     hidden_grid_dims
      - .offset:         312
        .size:           8
        .value_kind:     hidden_multigrid_sync_arg
      - .offset:         344
        .size:           4
        .value_kind:     hidden_dynamic_lds_size
    .group_segment_fixed_size: 0
    .kernarg_segment_align: 8
    .kernarg_segment_size: 480
    .language:       OpenCL C
    .language_version:
      - 2
      - 0
    .max_flat_workgroup_size: 512
    .name:           _Z9hymba_fwd4Args
    .private_segment_fixed_size: 0
    .sgpr_count:     108
    .sgpr_spill_count: 105
    .symbol:         _Z9hymba_fwd4Args.kd
    .uniform_work_group_size: 1
    .uses_dynamic_stack: false
    .vgpr_count:     256
    .vgpr_spill_count: 0
    .wavefront_size: 64
